# P3: accumulator zeroing pass removed too (first K-iteration peeled, C=0 MFMAs)
# speedup vs baseline: 1.0067x; 1.0067x over previous
; #define PG8_LAS __attribute__((address_space(3)))
; #define PG8_WAIT_V(n) asm volatile("s_waitcnt vmcnt(" #n ")" ::: "memory")
; #define PG8_BAR __builtin_amdgcn_s_barrier()
; template <class Epi, class Sched, bool ALIGN_EPI = false, bool SP2 = false, bool RS = false, bool BPRE = false>
; __device__ __forceinline__ void gemm_phase(PG8_LAS unsigned char* lds, const Gemm g, const Sched& S, const Epi& E, const float* rs_ss = nullptr, PG8_LAS float* rs_tab = nullptr) {
;     ...
;         const bool has_next = S.next(ui + 1, nxt);
;         const char* nA = has_next ? (const char*)g.A + (size_t)nxt.pm * tstep : cA; const char* nB = has_next ? (const char*)g.Bt + (size_t)nxt.pn * tstep : cB;
;         for (int t = 0; t < nt; t += 2) {
;             const bool last = (t == nt - 2);
;             if constexpr (RS) { if (t == 16 || t == 32) { const PG8_LAS float* tp = rs_tab + (ui & 1) * 768 + (t == 32 ? 256 : 0);
;                 _Pragma("unroll") for (int a = 0; a < 2; ++a) _Pragma("unroll") for (int m = 0; m < 4; ++m) { const float f = tp[a * HALF + wr * 64 + m * 16 + fr];
;                     _Pragma("unroll") for (int b = 0; b < 2; ++b) _Pragma("unroll") for (int n = 0; n < 2; ++n) acc[a][b][m][n] = acc[a][b][m][n] * f; } } }
;             const char* a1 = cA + (size_t)(t + 1) * kstep;
;             const char* a2 = last ? nA : cA + (size_t)(t + 2) * kstep; const char* b2 = last ? nB : cB + (size_t)(t + 2) * kstep;
;             const char* a3 = a2 + kstep; const char* b3 = b2 + kstep;
;             if (last && has_next) S.a_ready(nxt);
;             if constexpr (SP2) {
;             PG8_LDB(B0, 0, 0); PG8_LDB(B1, 0, 1); PG8_SCHED; PG8_LDA(At, 0, 0); PG8_STAGE(PG8_SA(1, 1), a1 + hstep, voffA);
;             PG8_WAIT_V(8); PG8_WAIT_L(0); PG8_BAR; PG8_MMA(0, 0, At, B0); PG8_MMA(0, 1, At, B1); PG8_BAR; PG8_SCHED;
;             PG8_LDA(At, 0, 1); PG8_STAGE(PG8_SB(0, 0), b2, voffB); PG8_STAGE(PG8_SB(0, 1), b2 + hstep, voffB); PG8_STAGE(PG8_SA(0, 0), a2, voffA);
;             PG8_WAIT_V(8); PG8_WAIT_L(0); PG8_BAR; PG8_MMA(1, 0, At, B0); PG8_MMA(1, 1, At, B1); PG8_BAR; PG8_SCHED;
;     ...
; #pragma unroll
;         for (int a = 0; a < 2; ++a)
; #pragma unroll
;             for (int b = 0; b < 2; ++b)
; #pragma unroll
;                 for (int m = 0; m < 4; ++m)
; #pragma unroll
;                     for (int n = 0; n < 2; ++n) acc[a][b][m][n] = (f32x4){0.f, 0.f, 0.f, 0.f};
.LBB0_751:
	s_bitcmp1_b32 s40, 0
	v_mov_b32_e32 v4, v2
	v_mov_b32_e32 v5, v2
	s_cselect_b32 s6, 0xc00, 0
	s_add_u32 s71, s38, 0x8000
	v_mov_b32_e32 v3, v2
	s_waitcnt lgkmcnt(0)
	s_waitcnt vmcnt(0)
	s_mov_b32 s73, 0
	v_add_u32_e32 v158, s6, v151
	v_lshl_add_u64 v[146:147], s[10:11], 0, v[138:139]
	v_lshl_add_u64 v[148:149], s[10:11], 0, v[140:141]
	s_addc_u32 s72, s39, 0
	s_mov_b64 s[6:7], 0
	s_add_u32 s38, s10, s6
	v_add_u32_e32 v3, s64, v150
	s_addc_u32 s39, s11, s7
	ds_read_b128 v[160:163], v3
	ds_read_b128 v[164:167], v3 offset:1024
	ds_read_b128 v[168:171], v3 offset:2048
	ds_read_b128 v[172:175], v3 offset:3072
	v_add_u32_e32 v3, s65, v150
	s_add_u32 s38, s38, 0x8000
	ds_read_b128 v[176:179], v3
	ds_read_b128 v[180:183], v3 offset:1024
	ds_read_b128 v[184:187], v3 offset:2048
	ds_read_b128 v[188:191], v3 offset:3072
	s_addc_u32 s39, s39, 0
	s_add_u32 s40, s71, s6
	s_addc_u32 s41, s72, s7
	s_cmp_eq_u32 s6, 0xb8000
	s_cselect_b32 s42, s20, s38
	s_cselect_b32 s43, s21, s39
	s_cselect_b32 s40, s36, s40
	s_cselect_b32 s41, s37, s41
	s_add_u32 s38, s42, 0x4000
	s_addc_u32 s39, s43, 0
	v_lshl_add_u64 v[4:5], v[146:147], 0, s[6:7]
	s_add_i32 m0, s55, 0xc000
	ds_read_b128 v[192:195], v154
	ds_read_b128 v[196:199], v154 offset:1024
	ds_read_b128 v[200:203], v154 offset:2048
	ds_read_b128 v[204:207], v154 offset:3072
	ds_read_b128 v[208:211], v154 offset:4096
	ds_read_b128 v[212:215], v154 offset:5120
	ds_read_b128 v[216:219], v154 offset:6144
	ds_read_b128 v[220:223], v154 offset:7168
	global_load_lds_dwordx4 v[4:5], off
	v_lshl_add_u64 v[4:5], v[148:149], 0, s[6:7]
	s_add_i32 m0, s55, 0xe000
	s_nop 0
	global_load_lds_dwordx4 v[4:5], off
	s_waitcnt vmcnt(8)
	s_waitcnt lgkmcnt(0)
	s_barrier
	s_setprio 1
	s_waitcnt lgkmcnt(0)
	v_mfma_f32_16x16x32_bf16 v[130:133], v[160:163], v[192:195], 0
	v_mfma_f32_16x16x32_bf16 v[126:129], v[168:171], v[192:195], 0
	v_mfma_f32_16x16x32_bf16 v[114:117], v[160:163], v[200:203], 0
	v_mfma_f32_16x16x32_bf16 v[110:113], v[168:171], v[200:203], 0
	v_mfma_f32_16x16x32_bf16 v[98:101], v[160:163], v[208:211], 0
	v_mfma_f32_16x16x32_bf16 v[94:97], v[168:171], v[208:211], 0
	v_mfma_f32_16x16x32_bf16 v[82:85], v[160:163], v[216:219], 0
	v_mfma_f32_16x16x32_bf16 v[78:81], v[168:171], v[216:219], 0
	v_mfma_f32_16x16x32_bf16 v[130:133], v[164:167], v[196:199], v[130:133]
	v_mfma_f32_16x16x32_bf16 v[126:129], v[172:175], v[196:199], v[126:129]
	v_mfma_f32_16x16x32_bf16 v[114:117], v[164:167], v[204:207], v[114:117]
	v_mfma_f32_16x16x32_bf16 v[110:113], v[172:175], v[204:207], v[110:113]
	v_mfma_f32_16x16x32_bf16 v[98:101], v[164:167], v[212:215], v[98:101]
	v_mfma_f32_16x16x32_bf16 v[94:97], v[172:175], v[212:215], v[94:97]
	v_mfma_f32_16x16x32_bf16 v[82:85], v[164:167], v[220:223], v[82:85]
	v_mfma_f32_16x16x32_bf16 v[78:81], v[172:175], v[220:223], v[78:81]
	s_setprio 0
	s_setprio 1
	v_mfma_f32_16x16x32_bf16 v[122:125], v[176:179], v[192:195], 0
	v_mfma_f32_16x16x32_bf16 v[118:121], v[184:187], v[192:195], 0
	v_mfma_f32_16x16x32_bf16 v[106:109], v[176:179], v[200:203], 0
	v_mfma_f32_16x16x32_bf16 v[102:105], v[184:187], v[200:203], 0
	v_mfma_f32_16x16x32_bf16 v[90:93], v[176:179], v[208:211], 0
	v_mfma_f32_16x16x32_bf16 v[86:89], v[184:187], v[208:211], 0
	v_mfma_f32_16x16x32_bf16 v[74:77], v[176:179], v[216:219], 0
	v_mfma_f32_16x16x32_bf16 v[70:73], v[184:187], v[216:219], 0
	v_mfma_f32_16x16x32_bf16 v[122:125], v[180:183], v[196:199], v[122:125]
	v_mfma_f32_16x16x32_bf16 v[118:121], v[188:191], v[196:199], v[118:121]
	v_mfma_f32_16x16x32_bf16 v[106:109], v[180:183], v[204:207], v[106:109]
	v_mfma_f32_16x16x32_bf16 v[102:105], v[188:191], v[204:207], v[102:105]
	v_mfma_f32_16x16x32_bf16 v[90:93], v[180:183], v[212:215], v[90:93]
	v_mfma_f32_16x16x32_bf16 v[86:89], v[188:191], v[212:215], v[86:89]
	v_mfma_f32_16x16x32_bf16 v[74:77], v[180:183], v[220:223], v[74:77]
	v_mfma_f32_16x16x32_bf16 v[70:73], v[188:191], v[220:223], v[70:73]
	s_setprio 0
	s_barrier
	s_add_i32 s74, s64, s54
	v_lshl_add_u64 v[4:5], s[40:41], 0, v[134:135]
	s_mov_b32 m0, s74
	ds_read_b128 v[192:195], v154 offset:16384
	ds_read_b128 v[196:199], v154 offset:17408
	ds_read_b128 v[200:203], v154 offset:18432
	ds_read_b128 v[204:207], v154 offset:19456
	ds_read_b128 v[208:211], v154 offset:20480
	ds_read_b128 v[212:215], v154 offset:21504
	ds_read_b128 v[216:219], v154 offset:22528
	ds_read_b128 v[220:223], v154 offset:23552
	global_load_lds_dwordx4 v[4:5], off
	s_add_i32 m0, s74, 0x2000
	s_add_u32 s74, s40, 0xc0000
	v_lshl_add_u64 v[4:5], s[40:41], 0, v[136:137]
	s_addc_u32 s75, s41, 0
	s_add_i32 s76, s65, s54
	global_load_lds_dwordx4 v[4:5], off
	v_lshl_add_u64 v[4:5], s[74:75], 0, v[134:135]
	s_mov_b32 m0, s76
	s_nop 0
	global_load_lds_dwordx4 v[4:5], off
	v_lshl_add_u64 v[4:5], s[74:75], 0, v[136:137]
	s_add_i32 m0, s76, 0x2000
	s_nop 0
	global_load_lds_dwordx4 v[4:5], off
	v_lshl_add_u64 v[4:5], s[42:43], 0, v[134:135]
	s_mov_b32 m0, s55
	s_nop 0
	global_load_lds_dwordx4 v[4:5], off
	v_lshl_add_u64 v[4:5], s[42:43], 0, v[136:137]
	s_mov_b32 m0, s56
	s_nop 0
	global_load_lds_dwordx4 v[4:5], off
	s_waitcnt vmcnt(8)
	s_waitcnt lgkmcnt(0)
	s_barrier
; #define PG8_STAGE(bufoff, gbase, voff) do { _Pragma("unroll") for (int _i = 0; _i < 2; ++_i) \
;         __builtin_amdgcn_global_load_lds((const unsigned*)((const char*)(gbase) + (voff)[_i]), (PG8_LAS unsigned*)(lds + (bufoff) + ldsw + _i * 8192), 16, 0, 0); } while (0)
; #define PG8_LDA(dst, b, h) do { _Pragma("unroll") for (int m = 0; m < 4; ++m) _Pragma("unroll") for (int k = 0; k < 2; ++k) dst[m][k] = *(const PG8_LAS bf16x8*)(lds + PG8_SA(b, h) + aoff + m * 2048 + k * 1024); } while (0)
; #define PG8_LDB(dst, b, h) do { _Pragma("unroll") for (int n = 0; n < 2; ++n) _Pragma("unroll") for (int k = 0; k < 2; ++k) dst[n][k] = *(const PG8_LAS bf16x8*)(lds + PG8_SB(b, h) + boff + n * 2048 + k * 1024); } while (0)
; #define PG8_MMA(ai, bj, At, Bt) do { __builtin_amdgcn_s_setprio(1); _Pragma("unroll") for (int m = 0; m < 4; ++m) _Pragma("unroll") for (int n = 0; n < 2; ++n) _Pragma("unroll") for (int k = 0; k < 2; ++k) \
;         acc[ai][bj][m][n] = __builtin_amdgcn_mfma_f32_16x16x32_bf16(Bt[n][k], At[m][k], acc[ai][bj][m][n], 0, 0, 0); __builtin_amdgcn_s_setprio(0); } while (0)
; #define PG8_WAIT_V(n) asm volatile("s_waitcnt vmcnt(" #n ")" ::: "memory")
; #define PG8_WAIT_L(n) asm volatile("s_waitcnt lgkmcnt(" #n ")" ::: "memory")
; #define PG8_BAR __builtin_amdgcn_s_barrier()
; #define PG8_SCHED __builtin_amdgcn_sched_barrier(0)
; template <class Epi, class Sched, bool ALIGN_EPI = false, bool SP2 = false, bool RS = false, bool BPRE = false>
; __device__ __forceinline__ void gemm_phase(PG8_LAS unsigned char* lds, const Gemm g, const Sched& S, const Epi& E, const float* rs_ss = nullptr, PG8_LAS float* rs_tab = nullptr) {
;     ...
;             PG8_WAIT_V(8); PG8_WAIT_L(0); PG8_BAR; PG8_MMA(0, 0, At, B0); PG8_MMA(0, 1, At, B1); PG8_BAR; PG8_SCHED;
;             PG8_LDA(At, 0, 1); PG8_STAGE(PG8_SB(0, 0), b2, voffB); PG8_STAGE(PG8_SB(0, 1), b2 + hstep, voffB); PG8_STAGE(PG8_SA(0, 0), a2, voffA);
;             PG8_WAIT_V(8); PG8_WAIT_L(0); PG8_BAR; PG8_MMA(1, 0, At, B0); PG8_MMA(1, 1, At, B1); PG8_BAR; PG8_SCHED;
;             PG8_LDB(B0, 1, 0); PG8_LDB(B1, 1, 1); PG8_SCHED; PG8_LDA(At, 1, 0); PG8_STAGE(PG8_SA(0, 1), a2 + hstep, voffA);
;             PG8_WAIT_V(8); PG8_WAIT_L(0); PG8_BAR; PG8_MMA(0, 0, At, B0); PG8_MMA(0, 1, At, B1); PG8_BAR; PG8_SCHED;
	s_setprio 1
	s_waitcnt lgkmcnt(0)
	v_mfma_f32_16x16x32_bf16 v[66:69], v[160:163], v[192:195], 0
	v_mfma_f32_16x16x32_bf16 v[62:65], v[168:171], v[192:195], 0
	v_mfma_f32_16x16x32_bf16 v[50:53], v[160:163], v[200:203], 0
	v_mfma_f32_16x16x32_bf16 v[46:49], v[168:171], v[200:203], 0
	v_mfma_f32_16x16x32_bf16 v[34:37], v[160:163], v[208:211], 0
	v_mfma_f32_16x16x32_bf16 v[30:33], v[168:171], v[208:211], 0
	v_mfma_f32_16x16x32_bf16 v[18:21], v[160:163], v[216:219], 0
	v_mfma_f32_16x16x32_bf16 v[14:17], v[168:171], v[216:219], 0
	v_mfma_f32_16x16x32_bf16 v[66:69], v[164:167], v[196:199], v[66:69]
	v_mfma_f32_16x16x32_bf16 v[62:65], v[172:175], v[196:199], v[62:65]
	v_mfma_f32_16x16x32_bf16 v[50:53], v[164:167], v[204:207], v[50:53]
	v_mfma_f32_16x16x32_bf16 v[46:49], v[172:175], v[204:207], v[46:49]
	v_mfma_f32_16x16x32_bf16 v[34:37], v[164:167], v[212:215], v[34:37]
	v_mfma_f32_16x16x32_bf16 v[30:33], v[172:175], v[212:215], v[30:33]
	v_mfma_f32_16x16x32_bf16 v[18:21], v[164:167], v[220:223], v[18:21]
	v_mfma_f32_16x16x32_bf16 v[14:17], v[172:175], v[220:223], v[14:17]
	s_setprio 0
	s_setprio 1
	v_mfma_f32_16x16x32_bf16 v[58:61], v[176:179], v[192:195], 0
	v_mfma_f32_16x16x32_bf16 v[54:57], v[184:187], v[192:195], 0
	v_mfma_f32_16x16x32_bf16 v[42:45], v[176:179], v[200:203], 0
	v_mfma_f32_16x16x32_bf16 v[38:41], v[184:187], v[200:203], 0
	v_mfma_f32_16x16x32_bf16 v[26:29], v[176:179], v[208:211], 0
	v_mfma_f32_16x16x32_bf16 v[22:25], v[184:187], v[208:211], 0
	v_mfma_f32_16x16x32_bf16 v[10:13], v[176:179], v[216:219], 0
	v_mfma_f32_16x16x32_bf16 v[4:7], v[184:187], v[216:219], 0
	v_mfma_f32_16x16x32_bf16 v[58:61], v[180:183], v[196:199], v[58:61]
	v_mfma_f32_16x16x32_bf16 v[54:57], v[188:191], v[196:199], v[54:57]
	v_mfma_f32_16x16x32_bf16 v[42:45], v[180:183], v[204:207], v[42:45]
	v_mfma_f32_16x16x32_bf16 v[38:41], v[188:191], v[204:207], v[38:41]
	v_mfma_f32_16x16x32_bf16 v[26:29], v[180:183], v[212:215], v[26:29]
	v_mfma_f32_16x16x32_bf16 v[22:25], v[188:191], v[212:215], v[22:25]
	v_mfma_f32_16x16x32_bf16 v[10:13], v[180:183], v[220:223], v[10:13]
	v_mfma_f32_16x16x32_bf16 v[4:7], v[188:191], v[220:223], v[4:7]
	s_setprio 0
	s_barrier
	s_add_i32 s74, 0, 0x18000
	v_add_u32_e32 v3, s74, v150
	s_add_i32 s75, 0, 0x1c000
	ds_read_b128 v[160:163], v3
	ds_read_b128 v[164:167], v3 offset:1024
	ds_read_b128 v[168:171], v3 offset:2048
	ds_read_b128 v[172:175], v3 offset:3072
	v_add_u32_e32 v3, s75, v150
	ds_read_b128 v[176:179], v3
	ds_read_b128 v[180:183], v3 offset:1024
	ds_read_b128 v[184:187], v3 offset:2048
	ds_read_b128 v[188:191], v3 offset:3072
	s_add_u32 s42, s42, 0xc0000
	s_addc_u32 s43, s43, 0
	s_mov_b32 m0, s57
	v_lshl_add_u64 v[8:9], s[42:43], 0, v[134:135]
	ds_read_b128 v[192:195], v154 offset:32768
	ds_read_b128 v[196:199], v154 offset:33792
	ds_read_b128 v[200:203], v154 offset:34816
	ds_read_b128 v[204:207], v154 offset:35840
	ds_read_b128 v[208:211], v154 offset:36864
	ds_read_b128 v[212:215], v154 offset:37888
	ds_read_b128 v[216:219], v154 offset:38912
	ds_read_b128 v[220:223], v154 offset:39936
	global_load_lds_dwordx4 v[8:9], off
	v_lshl_add_u64 v[8:9], s[42:43], 0, v[136:137]
	s_mov_b32 m0, s58
	s_nop 0
	global_load_lds_dwordx4 v[8:9], off
	s_waitcnt vmcnt(8)
	s_waitcnt lgkmcnt(0)
	s_barrier
	s_setprio 1
	s_waitcnt lgkmcnt(0)
	v_mfma_f32_16x16x32_bf16 v[130:133], v[160:163], v[192:195], v[130:133]
	v_mfma_f32_16x16x32_bf16 v[126:129], v[168:171], v[192:195], v[126:129]
	v_mfma_f32_16x16x32_bf16 v[114:117], v[160:163], v[200:203], v[114:117]
	v_mfma_f32_16x16x32_bf16 v[110:113], v[168:171], v[200:203], v[110:113]
	v_mfma_f32_16x16x32_bf16 v[98:101], v[160:163], v[208:211], v[98:101]
	v_mfma_f32_16x16x32_bf16 v[94:97], v[168:171], v[208:211], v[94:97]
	v_mfma_f32_16x16x32_bf16 v[82:85], v[160:163], v[216:219], v[82:85]
	v_mfma_f32_16x16x32_bf16 v[78:81], v[168:171], v[216:219], v[78:81]
	v_mfma_f32_16x16x32_bf16 v[130:133], v[164:167], v[196:199], v[130:133]
	v_mfma_f32_16x16x32_bf16 v[126:129], v[172:175], v[196:199], v[126:129]
	v_mfma_f32_16x16x32_bf16 v[114:117], v[164:167], v[204:207], v[114:117]
	v_mfma_f32_16x16x32_bf16 v[110:113], v[172:175], v[204:207], v[110:113]
	v_mfma_f32_16x16x32_bf16 v[98:101], v[164:167], v[212:215], v[98:101]
	v_mfma_f32_16x16x32_bf16 v[94:97], v[172:175], v[212:215], v[94:97]
	v_mfma_f32_16x16x32_bf16 v[82:85], v[164:167], v[220:223], v[82:85]
	v_mfma_f32_16x16x32_bf16 v[78:81], v[172:175], v[220:223], v[78:81]
	s_setprio 0
	s_setprio 1
	v_mfma_f32_16x16x32_bf16 v[122:125], v[176:179], v[192:195], v[122:125]
	v_mfma_f32_16x16x32_bf16 v[118:121], v[184:187], v[192:195], v[118:121]
	v_mfma_f32_16x16x32_bf16 v[106:109], v[176:179], v[200:203], v[106:109]
	v_mfma_f32_16x16x32_bf16 v[102:105], v[184:187], v[200:203], v[102:105]
	v_mfma_f32_16x16x32_bf16 v[90:93], v[176:179], v[208:211], v[90:93]
	v_mfma_f32_16x16x32_bf16 v[86:89], v[184:187], v[208:211], v[86:89]
	v_mfma_f32_16x16x32_bf16 v[74:77], v[176:179], v[216:219], v[74:77]
	v_mfma_f32_16x16x32_bf16 v[70:73], v[184:187], v[216:219], v[70:73]
	v_mfma_f32_16x16x32_bf16 v[122:125], v[180:183], v[196:199], v[122:125]
	v_mfma_f32_16x16x32_bf16 v[118:121], v[188:191], v[196:199], v[118:121]
	v_mfma_f32_16x16x32_bf16 v[106:109], v[180:183], v[204:207], v[106:109]
	v_mfma_f32_16x16x32_bf16 v[102:105], v[188:191], v[204:207], v[102:105]
	v_mfma_f32_16x16x32_bf16 v[90:93], v[180:183], v[212:215], v[90:93]
	v_mfma_f32_16x16x32_bf16 v[86:89], v[188:191], v[212:215], v[86:89]
	v_mfma_f32_16x16x32_bf16 v[74:77], v[180:183], v[220:223], v[74:77]
	v_mfma_f32_16x16x32_bf16 v[70:73], v[188:191], v[220:223], v[70:73]
	s_setprio 0
	s_barrier
; #define PG8_STAGE(bufoff, gbase, voff) do { _Pragma("unroll") for (int _i = 0; _i < 2; ++_i) \
;         __builtin_amdgcn_global_load_lds((const unsigned*)((const char*)(gbase) + (voff)[_i]), (PG8_LAS unsigned*)(lds + (bufoff) + ldsw + _i * 8192), 16, 0, 0); } while (0)
; #define PG8_LDA(dst, b, h) do { _Pragma("unroll") for (int m = 0; m < 4; ++m) _Pragma("unroll") for (int k = 0; k < 2; ++k) dst[m][k] = *(const PG8_LAS bf16x8*)(lds + PG8_SA(b, h) + aoff + m * 2048 + k * 1024); } while (0)
; #define PG8_LDB(dst, b, h) do { _Pragma("unroll") for (int n = 0; n < 2; ++n) _Pragma("unroll") for (int k = 0; k < 2; ++k) dst[n][k] = *(const PG8_LAS bf16x8*)(lds + PG8_SB(b, h) + boff + n * 2048 + k * 1024); } while (0)
; #define PG8_MMA(ai, bj, At, Bt) do { __builtin_amdgcn_s_setprio(1); _Pragma("unroll") for (int m = 0; m < 4; ++m) _Pragma("unroll") for (int n = 0; n < 2; ++n) _Pragma("unroll") for (int k = 0; k < 2; ++k) \
;         acc[ai][bj][m][n] = __builtin_amdgcn_mfma_f32_16x16x32_bf16(Bt[n][k], At[m][k], acc[ai][bj][m][n], 0, 0, 0); __builtin_amdgcn_s_setprio(0); } while (0)
; #define PG8_WAIT_V(n) asm volatile("s_waitcnt vmcnt(" #n ")" ::: "memory")
; #define PG8_WAIT_L(n) asm volatile("s_waitcnt lgkmcnt(" #n ")" ::: "memory")
; #define PG8_BAR __builtin_amdgcn_s_barrier()
; #define PG8_SCHED __builtin_amdgcn_sched_barrier(0)
; template <class Epi, class Sched, bool ALIGN_EPI = false, bool SP2 = false, bool RS = false, bool BPRE = false>
; __device__ __forceinline__ void gemm_phase(PG8_LAS unsigned char* lds, const Gemm g, const Sched& S, const Epi& E, const float* rs_ss = nullptr, PG8_LAS float* rs_tab = nullptr) {
;     ...
;             PG8_LDB(B0, 1, 0); PG8_LDB(B1, 1, 1); PG8_SCHED; PG8_LDA(At, 1, 0); PG8_STAGE(PG8_SA(0, 1), a2 + hstep, voffA);
;             PG8_WAIT_V(8); PG8_WAIT_L(0); PG8_BAR; PG8_MMA(0, 0, At, B0); PG8_MMA(0, 1, At, B1); PG8_BAR; PG8_SCHED;
;             PG8_LDA(At, 1, 1); PG8_STAGE(PG8_SB(1, 0), b3, voffB); PG8_STAGE(PG8_SB(1, 1), b3 + hstep, voffB); PG8_STAGE(PG8_SA(1, 0), a3, voffA);
;             PG8_WAIT_V(8); PG8_WAIT_L(0); PG8_BAR; PG8_MMA(1, 0, At, B0); PG8_MMA(1, 1, At, B1); PG8_BAR; PG8_SCHED;
	s_add_u32 s42, s40, 0x4000
	s_addc_u32 s43, s41, 0
	s_add_i32 s74, s74, s54
	v_lshl_add_u64 v[8:9], s[42:43], 0, v[134:135]
	s_mov_b32 m0, s74
	ds_read_b128 v[192:195], v154 offset:49152
	ds_read_b128 v[196:199], v154 offset:50176
	ds_read_b128 v[200:203], v154 offset:51200
	ds_read_b128 v[204:207], v154 offset:52224
	ds_read_b128 v[208:211], v154 offset:53248
	ds_read_b128 v[212:215], v154 offset:54272
	ds_read_b128 v[216:219], v154 offset:55296
	ds_read_b128 v[220:223], v154 offset:56320
	global_load_lds_dwordx4 v[8:9], off
	s_add_i32 m0, s74, 0x2000
	s_add_u32 s40, s40, 0xc4000
	v_lshl_add_u64 v[8:9], s[42:43], 0, v[136:137]
	s_addc_u32 s41, s41, 0
	s_add_i32 s42, s75, s54
	global_load_lds_dwordx4 v[8:9], off
	v_lshl_add_u64 v[8:9], s[40:41], 0, v[134:135]
	s_mov_b32 m0, s42
	s_nop 0
	global_load_lds_dwordx4 v[8:9], off
	v_lshl_add_u64 v[8:9], s[40:41], 0, v[136:137]
	s_add_i32 m0, s42, 0x2000
	s_nop 0
	global_load_lds_dwordx4 v[8:9], off
	v_lshl_add_u64 v[8:9], s[38:39], 0, v[134:135]
	s_mov_b32 m0, s60
	s_nop 0
	global_load_lds_dwordx4 v[8:9], off
	v_lshl_add_u64 v[8:9], s[38:39], 0, v[136:137]
	s_mov_b32 m0, s61
	s_nop 0
	global_load_lds_dwordx4 v[8:9], off
	s_waitcnt vmcnt(8)
	s_waitcnt lgkmcnt(0)
	s_barrier
	s_setprio 1
	s_waitcnt lgkmcnt(0)
	v_mfma_f32_16x16x32_bf16 v[66:69], v[160:163], v[192:195], v[66:69]
	v_mfma_f32_16x16x32_bf16 v[62:65], v[168:171], v[192:195], v[62:65]
	v_mfma_f32_16x16x32_bf16 v[50:53], v[160:163], v[200:203], v[50:53]
	v_mfma_f32_16x16x32_bf16 v[46:49], v[168:171], v[200:203], v[46:49]
	v_mfma_f32_16x16x32_bf16 v[34:37], v[160:163], v[208:211], v[34:37]
	v_mfma_f32_16x16x32_bf16 v[30:33], v[168:171], v[208:211], v[30:33]
	v_mfma_f32_16x16x32_bf16 v[18:21], v[160:163], v[216:219], v[18:21]
	v_mfma_f32_16x16x32_bf16 v[14:17], v[168:171], v[216:219], v[14:17]
	v_mfma_f32_16x16x32_bf16 v[66:69], v[164:167], v[196:199], v[66:69]
	v_mfma_f32_16x16x32_bf16 v[62:65], v[172:175], v[196:199], v[62:65]
	v_mfma_f32_16x16x32_bf16 v[50:53], v[164:167], v[204:207], v[50:53]
	v_mfma_f32_16x16x32_bf16 v[46:49], v[172:175], v[204:207], v[46:49]
	v_mfma_f32_16x16x32_bf16 v[34:37], v[164:167], v[212:215], v[34:37]
	v_mfma_f32_16x16x32_bf16 v[30:33], v[172:175], v[212:215], v[30:33]
	v_mfma_f32_16x16x32_bf16 v[18:21], v[164:167], v[220:223], v[18:21]
	v_mfma_f32_16x16x32_bf16 v[14:17], v[172:175], v[220:223], v[14:17]
	s_setprio 0
	s_setprio 1
	v_mfma_f32_16x16x32_bf16 v[58:61], v[176:179], v[192:195], v[58:61]
	v_mfma_f32_16x16x32_bf16 v[54:57], v[184:187], v[192:195], v[54:57]
	v_mfma_f32_16x16x32_bf16 v[42:45], v[176:179], v[200:203], v[42:45]
	v_mfma_f32_16x16x32_bf16 v[38:41], v[184:187], v[200:203], v[38:41]
	v_mfma_f32_16x16x32_bf16 v[26:29], v[176:179], v[208:211], v[26:29]
	v_mfma_f32_16x16x32_bf16 v[22:25], v[184:187], v[208:211], v[22:25]
	v_mfma_f32_16x16x32_bf16 v[8:11], v[176:179], v[216:219], v[10:13]
	v_mfma_f32_16x16x32_bf16 v[4:7], v[184:187], v[216:219], v[4:7]
	v_mfma_f32_16x16x32_bf16 v[58:61], v[180:183], v[196:199], v[58:61]
	v_mfma_f32_16x16x32_bf16 v[54:57], v[188:191], v[196:199], v[54:57]
	v_mfma_f32_16x16x32_bf16 v[42:45], v[180:183], v[204:207], v[42:45]
	v_mfma_f32_16x16x32_bf16 v[38:41], v[188:191], v[204:207], v[38:41]
	v_mfma_f32_16x16x32_bf16 v[26:29], v[180:183], v[212:215], v[26:29]
	v_mfma_f32_16x16x32_bf16 v[22:25], v[188:191], v[212:215], v[22:25]
	v_mfma_f32_16x16x32_bf16 v[10:13], v[180:183], v[220:223], v[8:11]
	v_mfma_f32_16x16x32_bf16 v[6:9], v[188:191], v[220:223], v[4:7]
	s_setprio 0
	s_barrier
	s_add_i32 s38, s73, 2
	s_add_u32 s6, s6, 0x8000
	s_addc_u32 s7, s7, 0
	s_cmp_gt_u32 s73, 45
	s_mov_b32 s73, s38
	s_branch .LBB0_753
